# first seam: P0 results stored write-through (sc1) so no L2 write-back in the barrier; L1 invalidate issued at arrival
# baseline (speedup 1.0000x reference)
; DI void phase0(const float* cvec, const float* ada_w, const float* w_in, const float* w_out, bf16* WIN, bf16* WOUT, float* MODP, float* KMAX, bf16* WDT,
;                LAS unsigned char* lds, int tid, int G) {
;     ...
;     if (blockIdx.x == 0) for (int i = tid; i < 2 * 8 * 128; i += 512) KMAX[i] = 0.f;
.LBB0_21:
	v_add_u32_e32 v7, -2, v7
	v_ashrrev_i32_e32 v11, 31, v3
	v_mov_b32_e32 v10, v3
	v_ashrrev_i32_e32 v13, 31, v2
	v_mov_b32_e32 v12, v2
	v_cmp_eq_u32_e32 vcc, 0, v7
	v_add_u32_e32 v3, 0x400, v3
	v_add_u32_e32 v2, 0x400, v2
	v_lshl_add_u64 v[12:13], v[12:13], 2, s[68:69]
	v_lshl_add_u64 v[10:11], v[10:11], 2, s[68:69]
	s_or_b64 s[8:9], vcc, s[8:9]
	global_store_dword v[12:13], v6, off sc1
	global_store_dword v[10:11], v6, off sc1
	s_andn2_b64 exec, exec, s[8:9]
	s_cbranch_execnz .LBB0_21
	s_or_b64 exec, exec, s[8:9]
	v_cmp_ne_u32_e32 vcc, v4, v5
	v_lshl_add_u32 v2, v5, 9, v0
	s_orn2_b64 s[8:9], vcc, exec

; DI void phase0(const float* cvec, const float* ada_w, const float* w_in, const float* w_out, bf16* WIN, bf16* WOUT, float* MODP, float* KMAX, bf16* WDT,
;                LAS unsigned char* lds, int tid, int G) {
;     ...
;     if (blockIdx.x == 0) for (int i = tid; i < 2 * 8 * 128; i += 512) KMAX[i] = 0.f;
.LBB0_25:
	v_add_u32_e32 v1, 0x200, v1
	v_cmp_lt_i32_e32 vcc, s10, v1
	global_store_dword v[2:3], v4, off sc1
	s_or_b64 s[6:7], vcc, s[6:7]
	v_lshl_add_u64 v[2:3], v[2:3], 0, s[8:9]
	s_andn2_b64 exec, exec, s[6:7]
	s_cbranch_execnz .LBB0_25

; DI unsigned pk2(float lo, float hi) { f32x2_t v = {lo, hi}; bf16x2_t b = __builtin_convertvector(v, bf16x2_t); return __builtin_bit_cast(unsigned, b); }
; DI void phase0(const float* cvec, const float* ada_w, const float* w_in, const float* w_out, bf16* WIN, bf16* WOUT, float* MODP, float* KMAX, bf16* WDT,
;                LAS unsigned char* lds, int tid, int G) {
;     ...
;     for (int i = blockIdx.x * 512 + tid; i < 32768; i += G * 512) { const int l = i >> 14, jj = (i >> 10) & 15, col = i & 1023;
;         WDT[i] = jj < 8 ? (bf16)(pk2(w_in[((size_t)l * 1024 + col) * DIN + 3072 + jj], 0.f) & 0xffffu) : (bf16)0; }
.LBB0_28:
	s_or_b64 exec, exec, s[12:13]
	v_add_u32_e32 v2, s6, v2
	v_cmp_lt_i32_e32 vcc, s14, v2
	global_store_short v[4:5], v3, off sc1
	s_or_b64 s[10:11], vcc, s[10:11]
	v_lshl_add_u64 v[4:5], v[4:5], 0, s[8:9]
	s_andn2_b64 exec, exec, s[10:11]
	s_cbranch_execz .LBB0_31

; #define LAS __attribute__((address_space(3)))
; DI unsigned pk2(float lo, float hi) { f32x2_t v = {lo, hi}; bf16x2_t b = __builtin_convertvector(v, bf16x2_t); return __builtin_bit_cast(unsigned, b); }
; #define LDS_WAIT() asm volatile("s_waitcnt lgkmcnt(0)" ::: "memory")
; DI void p0_transpose_item(const float* W, int ldw, int srccol, float scale, bf16* WT, int k0, LAS float* scr, int lane) {
;     f32x4 wv[8];
; #pragma unroll
;     for (int i = 0; i < 8; ++i) wv[i] = __builtin_nontemporal_load((const f32x4*)(W + (size_t)(k0 + 8 * i + (lane >> 3)) * ldw + srccol + 4 * (lane & 7)));
; #pragma unroll
;     for (int i = 0; i < 8; ++i) { LAS float* d = scr + (8 * i + (lane >> 3)) * 33 + 4 * (lane & 7);
;         d[0] = wv[i][0] * scale; d[1] = wv[i][1] * scale; d[2] = wv[i][2] * scale; d[3] = wv[i][3] * scale; }
;     LDS_WAIT();
;     const int c = lane & 7;
; #pragma unroll
;     for (int j = 0; j < 4; ++j) { const int n = (lane >> 3) + 8 * j; const LAS float* s = scr + (8 * c) * 33 + n;
;         u32x4 o; o.x = pk2(s[0 * 33], s[1 * 33]); o.y = pk2(s[2 * 33], s[3 * 33]); o.z = pk2(s[4 * 33], s[5 * 33]); o.w = pk2(s[6 * 33], s[7 * 33]);
;         *(u32x4*)(WT + (size_t)n * 1024 + k0 + 8 * c) = o; }
;     LDS_WAIT();
; }
; DI void phase0(const float* cvec, const float* ada_w, const float* w_in, const float* w_out, bf16* WIN, bf16* WOUT, float* MODP, float* KMAX, bf16* WDT,
;                LAS unsigned char* lds, int tid, int G) {
;     ...
;             r -= I_IN; const int kb = r >> 5, nb = r & 31, n0 = 32 * nb;
;             p0_transpose_item(w_out + (size_t)l * 1024 * 1024, 1024, n0, 1.f, WOUT + ((size_t)l * 1024 + n0) * 1024, 64 * kb, scr, lane);
.LBB0_34:
	v_mul_hi_i32 v2, v18, s12
	v_lshrrev_b32_e32 v5, 31, v2
	v_ashrrev_i32_e32 v2, 10, v2
	v_add_u32_e32 v16, v2, v5
	v_mad_i32_i24 v5, v16, s13, v18
	v_cmp_lt_i32_e32 vcc, s14, v5
	v_ashrrev_i32_e32 v17, 31, v16
	s_and_saveexec_b64 s[8:9], vcc
	s_xor_b64 s[8:9], exec, s[8:9]
	s_cbranch_execz .LBB0_36
	v_readlane_b32 s22, v253, 21
	v_and_b32_e32 v7, 0x3e0, v21
	v_lshlrev_b64 v[40:41], 22, v[16:17]
	v_lshlrev_b64 v[16:17], 21, v[16:17]
	v_readlane_b32 s23, v253, 22
	v_lshlrev_b32_e32 v2, 11, v7
	v_readlane_b32 s52, v253, 5
	v_lshl_add_u64 v[16:17], s[22:23], 0, v[16:17]
	v_lshl_add_u64 v[16:17], v[16:17], 0, v[2:3]
	v_lshlrev_b32_e32 v2, 1, v5
	v_and_b32_e32 v2, 0xffffffc0, v2
	v_add_u32_e32 v74, 0xfffff000, v2
	v_readlane_b32 s66, v253, 19
	v_readlane_b32 s67, v253, 20
	v_or_b32_e32 v70, v74, v19
	v_lshlrev_b32_e32 v2, 2, v7
	v_lshl_add_u64 v[40:41], s[66:67], 0, v[40:41]
	v_or_b32_e32 v42, 8, v70
	v_or_b32_e32 v48, 16, v70
	v_or_b32_e32 v50, 24, v70
	v_or_b32_e32 v58, 32, v70
	v_or_b32_e32 v60, 40, v70
	v_lshl_add_u64 v[40:41], v[40:41], 0, v[2:3]
	v_mov_b32_e32 v5, v3
	v_ashrrev_i32_e32 v71, 31, v70
	v_ashrrev_i32_e32 v43, 31, v42
	v_ashrrev_i32_e32 v49, 31, v48
	v_ashrrev_i32_e32 v51, 31, v50
	v_ashrrev_i32_e32 v59, 31, v58
	v_ashrrev_i32_e32 v61, 31, v60
	v_lshl_add_u64 v[72:73], v[40:41], 0, v[4:5]
	v_lshlrev_b64 v[40:41], 12, v[70:71]
	v_lshlrev_b64 v[42:43], 12, v[42:43]
	v_lshlrev_b64 v[48:49], 12, v[48:49]
	v_lshlrev_b64 v[50:51], 12, v[50:51]
	v_lshlrev_b64 v[58:59], 12, v[58:59]
	v_lshlrev_b64 v[60:61], 12, v[60:61]
	v_lshl_add_u64 v[40:41], v[72:73], 0, v[40:41]
	v_lshl_add_u64 v[44:45], v[72:73], 0, v[42:43]
	v_lshl_add_u64 v[48:49], v[72:73], 0, v[48:49]
	v_lshl_add_u64 v[54:55], v[72:73], 0, v[50:51]
	v_lshl_add_u64 v[58:59], v[72:73], 0, v[58:59]
	v_lshl_add_u64 v[62:63], v[72:73], 0, v[60:61]
	global_load_dwordx4 v[40:43], v[40:41], off nt
	s_nop 0
	global_load_dwordx4 v[44:47], v[44:45], off nt
	s_nop 0
	global_load_dwordx4 v[48:51], v[48:49], off nt
	s_nop 0
	global_load_dwordx4 v[54:57], v[54:55], off nt
	s_nop 0
	global_load_dwordx4 v[58:61], v[58:59], off nt
	s_nop 0
	global_load_dwordx4 v[62:65], v[62:63], off nt
	v_or_b32_e32 v66, 48, v70
	v_ashrrev_i32_e32 v67, 31, v66
	v_lshlrev_b64 v[66:67], 12, v[66:67]
	v_or_b32_e32 v70, 56, v70
	v_lshl_add_u64 v[66:67], v[72:73], 0, v[66:67]
	v_ashrrev_i32_e32 v71, 31, v70
	global_load_dwordx4 v[66:69], v[66:67], off nt
	v_lshlrev_b64 v[70:71], 12, v[70:71]
	v_lshl_add_u64 v[70:71], v[72:73], 0, v[70:71]
	global_load_dwordx4 v[70:73], v[70:71], off nt
	v_ashrrev_i32_e32 v75, 31, v74
	v_mov_b32_e32 v7, v3
	v_lshl_add_u64 v[16:17], v[74:75], 1, v[16:17]
	v_mov_b32_e32 v9, v3
	v_lshl_add_u64 v[16:17], v[16:17], 0, v[6:7]
	v_lshl_add_u64 v[74:75], v[16:17], 0, v[8:9]
	v_mov_b32_e32 v11, v3
	v_lshl_add_u64 v[76:77], v[16:17], 0, v[10:11]
	v_mov_b32_e32 v13, v3
	v_mov_b32_e32 v15, v3
	v_readlane_b32 s58, v253, 11
	v_readlane_b32 s59, v253, 12
	v_readlane_b32 s58, v253, 24
	v_readlane_b32 s53, v253, 6
	v_readlane_b32 s54, v253, 7
	v_readlane_b32 s55, v253, 8
	v_readlane_b32 s56, v253, 9
	v_readlane_b32 s57, v253, 10
	v_readlane_b32 s60, v253, 13
	v_readlane_b32 s61, v253, 14
	v_readlane_b32 s62, v253, 15
	v_readlane_b32 s63, v253, 16
	v_readlane_b32 s64, v253, 17
	v_readlane_b32 s65, v253, 18
	v_readlane_b32 s59, v253, 25
	v_readlane_b32 s66, v253, 23
	s_waitcnt vmcnt(7)
	ds_write2_b32 v22, v40, v41 offset1:1
	ds_write2_b32 v22, v42, v43 offset0:2 offset1:3
	s_waitcnt vmcnt(6)
	ds_write2_b32 v23, v44, v45 offset1:1
	ds_write2_b32 v24, v46, v47 offset1:1
	s_waitcnt vmcnt(5)
	ds_write2_b32 v25, v48, v49 offset1:1
	ds_write2_b32 v26, v50, v51 offset1:1
	s_waitcnt vmcnt(4)
	ds_write2_b32 v27, v54, v55 offset1:1
	ds_write2_b32 v28, v56, v57 offset1:1
	s_waitcnt vmcnt(3)
	ds_write2_b32 v29, v58, v59 offset1:1
	ds_write2_b32 v30, v60, v61 offset1:1
	s_waitcnt vmcnt(2)
	ds_write2_b32 v31, v62, v63 offset1:1
	ds_write2_b32 v32, v64, v65 offset1:1
	s_waitcnt vmcnt(1)
	ds_write2_b32 v33, v66, v67 offset1:1
	ds_write2_b32 v34, v68, v69 offset1:1
	s_waitcnt vmcnt(0)
	ds_write2_b32 v35, v70, v71 offset1:1
	ds_write2_b32 v37, v72, v73 offset1:1
	s_waitcnt lgkmcnt(0)
	ds_read2_b32 v[44:45], v20 offset0:33 offset1:41
	ds_read2_b32 v[46:47], v20 offset1:8
	ds_read2_b32 v[48:49], v20 offset0:66 offset1:74
	ds_read2_b32 v[50:51], v20 offset0:99 offset1:107
	ds_read2_b32 v[54:55], v20 offset0:132 offset1:140
	ds_read2_b32 v[56:57], v20 offset0:165 offset1:173
	ds_read2_b32 v[58:59], v20 offset0:198 offset1:206
	ds_read2_b32 v[60:61], v20 offset0:231 offset1:239
	ds_read2_b32 v[62:63], v20 offset0:49 offset1:57
	s_waitcnt lgkmcnt(7)
	v_cvt_pk_bf16_f32 v40, v46, v44
	s_waitcnt lgkmcnt(5)
	v_cvt_pk_bf16_f32 v41, v48, v50
	s_waitcnt lgkmcnt(3)
	v_cvt_pk_bf16_f32 v42, v54, v56
	s_waitcnt lgkmcnt(1)
	v_cvt_pk_bf16_f32 v43, v58, v60
	global_store_dwordx4 v[74:75], v[40:43], off sc1
	v_cvt_pk_bf16_f32 v44, v47, v45
	v_cvt_pk_bf16_f32 v45, v49, v51
	v_cvt_pk_bf16_f32 v46, v55, v57
	v_cvt_pk_bf16_f32 v47, v59, v61
	ds_read2_b32 v[48:49], v20 offset0:16 offset1:24
	ds_read2_b32 v[50:51], v20 offset0:82 offset1:90
	ds_read2_b32 v[54:55], v20 offset0:115 offset1:123
	ds_read2_b32 v[56:57], v20 offset0:148 offset1:156
	ds_read2_b32 v[58:59], v20 offset0:181 offset1:189
	ds_read2_b32 v[60:61], v20 offset0:214 offset1:222
	ds_read2_b32 v[64:65], v20 offset0:247 offset1:255
	global_store_dwordx4 v[76:77], v[44:47], off sc1
	s_waitcnt lgkmcnt(6)
	v_cvt_pk_bf16_f32 v40, v48, v62
	s_waitcnt lgkmcnt(4)
	v_cvt_pk_bf16_f32 v41, v50, v54
	s_waitcnt lgkmcnt(2)
	v_cvt_pk_bf16_f32 v42, v56, v58
	s_waitcnt lgkmcnt(0)
	v_cvt_pk_bf16_f32 v43, v60, v64
	v_lshl_add_u64 v[44:45], v[16:17], 0, v[12:13]
	global_store_dwordx4 v[44:45], v[40:43], off sc1
	v_lshl_add_u64 v[16:17], v[16:17], 0, v[14:15]
	s_nop 0
	v_cvt_pk_bf16_f32 v40, v49, v63
	v_cvt_pk_bf16_f32 v41, v51, v55
	v_cvt_pk_bf16_f32 v42, v57, v59
	v_cvt_pk_bf16_f32 v43, v61, v65
	global_store_dwordx4 v[16:17], v[40:43], off sc1
	s_waitcnt lgkmcnt(0)
; #define LAS __attribute__((address_space(3)))
; DI unsigned pk2(float lo, float hi) { f32x2_t v = {lo, hi}; bf16x2_t b = __builtin_convertvector(v, bf16x2_t); return __builtin_bit_cast(unsigned, b); }
; #define LDS_WAIT() asm volatile("s_waitcnt lgkmcnt(0)" ::: "memory")
; DI void p0_transpose_item(const float* W, int ldw, int srccol, float scale, bf16* WT, int k0, LAS float* scr, int lane) {
;     f32x4 wv[8];
; #pragma unroll
;     for (int i = 0; i < 8; ++i) wv[i] = __builtin_nontemporal_load((const f32x4*)(W + (size_t)(k0 + 8 * i + (lane >> 3)) * ldw + srccol + 4 * (lane & 7)));
; #pragma unroll
;     for (int i = 0; i < 8; ++i) { LAS float* d = scr + (8 * i + (lane >> 3)) * 33 + 4 * (lane & 7);
;         d[0] = wv[i][0] * scale; d[1] = wv[i][1] * scale; d[2] = wv[i][2] * scale; d[3] = wv[i][3] * scale; }
;     LDS_WAIT();
;     const int c = lane & 7;
; #pragma unroll
;     for (int j = 0; j < 4; ++j) { const int n = (lane >> 3) + 8 * j; const LAS float* s = scr + (8 * c) * 33 + n;
;         u32x4 o; o.x = pk2(s[0 * 33], s[1 * 33]); o.y = pk2(s[2 * 33], s[3 * 33]); o.z = pk2(s[4 * 33], s[5 * 33]); o.w = pk2(s[6 * 33], s[7 * 33]);
;         *(u32x4*)(WT + (size_t)n * 1024 + k0 + 8 * c) = o; }
;     LDS_WAIT();
; }
; DI void phase0(const float* cvec, const float* ada_w, const float* w_in, const float* w_out, bf16* WIN, bf16* WOUT, float* MODP, float* KMAX, bf16* WDT,
;                LAS unsigned char* lds, int tid, int G) {
;     ...
;             const int kb = r >> 7, nb = r & 127, n0 = 32 * nb; const int src = n0 + (n0 >= 3072 ? 8 : 0);
;             float sc = 1.f;
;             if (n0 < 256) sc = 0.125f * LOG2E; else if (n0 >= 1024 && n0 < 1280) sc = 0.17677669529663687f * LOG2E; else if (n0 >= 3072 && n0 < 3328) sc = 0.125f * LOG2E;
;             p0_transpose_item(w_in + (size_t)l * 1024 * DIN, DIN, src, sc, WIN + ((size_t)l * NP + n0) * 1024, 64 * kb, scr, lane);
.LBB0_36:
	s_andn2_saveexec_b64 s[8:9], s[8:9]
	s_cbranch_execz .LBB0_33
	v_and_b32_e32 v7, 0xfe0, v21
	v_cmp_lt_u32_e32 vcc, s15, v7
	v_mov_b64_e32 v[40:41], s[46:47]
	v_mad_i64_i32 v[40:41], s[22:23], v16, s18, v[40:41]
	v_cndmask_b32_e64 v2, 0, 8, vcc
	v_lshlrev_b64 v[16:17], 23, v[16:17]
	v_or_b32_e32 v9, v2, v7
	v_lshl_add_u64 v[16:17], s[80:81], 0, v[16:17]
	v_lshlrev_b32_e32 v2, 11, v7
	v_lshl_add_u64 v[16:17], v[16:17], 0, v[2:3]
	v_ashrrev_i32_e32 v2, 1, v5
	v_and_b32_e32 v74, 0xffffffc0, v2
	v_lshlrev_b32_e32 v2, 2, v9
	v_or_b32_e32 v11, v74, v19
	v_lshl_add_u64 v[40:41], v[40:41], 0, v[2:3]
	v_mov_b32_e32 v5, v3
	v_lshl_add_u64 v[70:71], v[40:41], 0, v[4:5]
	v_or_b32_e32 v2, 8, v11
	v_mad_i64_i32 v[44:45], s[22:23], v2, s19, v[70:71]
	v_or_b32_e32 v2, 16, v11
	v_or_b32_e32 v5, 24, v11
	v_mad_i64_i32 v[48:49], s[22:23], v2, s19, v[70:71]
	v_mad_i64_i32 v[54:55], s[22:23], v5, s19, v[70:71]
	v_or_b32_e32 v2, 32, v11
	v_or_b32_e32 v5, 40, v11
	v_mad_i64_i32 v[58:59], s[22:23], v2, s19, v[70:71]
	v_mad_i64_i32 v[62:63], s[22:23], v5, s19, v[70:71]
	v_or_b32_e32 v2, 48, v11
	v_or_b32_e32 v5, 56, v11
	v_mad_i64_i32 v[40:41], s[22:23], v11, s19, v[70:71]
	v_mad_i64_i32 v[66:67], s[22:23], v2, s19, v[70:71]
	v_mad_i64_i32 v[70:71], s[22:23], v5, s19, v[70:71]
	global_load_dwordx4 v[40:43], v[40:41], off nt
	s_nop 0
	global_load_dwordx4 v[44:47], v[44:45], off nt
	s_nop 0
	global_load_dwordx4 v[48:51], v[48:49], off nt
	s_nop 0
	global_load_dwordx4 v[54:57], v[54:55], off nt
	s_nop 0
	global_load_dwordx4 v[58:61], v[58:59], off nt
	s_nop 0
	global_load_dwordx4 v[62:65], v[62:63], off nt
	v_and_b32_e32 v2, 0x78, v18
	global_load_dwordx4 v[66:69], v[66:67], off nt
	v_cmp_eq_u32_e32 vcc, s16, v2
	global_load_dwordx4 v[70:73], v[70:71], off nt
	v_ashrrev_i32_e32 v75, 31, v74
	v_cndmask_b32_e32 v5, 1.0, v38, vcc
	v_cmp_ne_u32_e32 vcc, 32, v2
	v_lshl_add_u64 v[16:17], v[74:75], 1, v[16:17]
	v_mov_b32_e32 v9, v3
	v_cndmask_b32_e32 v2, v39, v5, vcc
	v_cmp_lt_u32_e32 vcc, s17, v7
	v_mov_b32_e32 v7, v3
	v_lshl_add_u64 v[16:17], v[16:17], 0, v[6:7]
	v_cndmask_b32_e32 v2, v38, v2, vcc
	v_mov_b32_e32 v11, v3
	v_mov_b32_e32 v13, v3
	v_mov_b32_e32 v15, v3
	s_waitcnt vmcnt(7)
	v_pk_mul_f32 v[40:41], v[2:3], v[40:41] op_sel_hi:[0,1]
	v_pk_mul_f32 v[42:43], v[2:3], v[42:43] op_sel_hi:[0,1]
	s_waitcnt vmcnt(6)
	v_pk_mul_f32 v[44:45], v[2:3], v[44:45] op_sel_hi:[0,1]
	v_pk_mul_f32 v[46:47], v[2:3], v[46:47] op_sel_hi:[0,1]
	s_waitcnt vmcnt(5)
	v_pk_mul_f32 v[48:49], v[2:3], v[48:49] op_sel_hi:[0,1]
	v_pk_mul_f32 v[50:51], v[2:3], v[50:51] op_sel_hi:[0,1]
	s_waitcnt vmcnt(4)
	v_pk_mul_f32 v[54:55], v[2:3], v[54:55] op_sel_hi:[0,1]
	v_pk_mul_f32 v[56:57], v[2:3], v[56:57] op_sel_hi:[0,1]
	s_waitcnt vmcnt(3)
	v_pk_mul_f32 v[58:59], v[2:3], v[58:59] op_sel_hi:[0,1]
	v_pk_mul_f32 v[60:61], v[2:3], v[60:61] op_sel_hi:[0,1]
	s_waitcnt vmcnt(2)
	v_pk_mul_f32 v[62:63], v[2:3], v[62:63] op_sel_hi:[0,1]
	v_pk_mul_f32 v[64:65], v[2:3], v[64:65] op_sel_hi:[0,1]
	s_waitcnt vmcnt(1)
	v_pk_mul_f32 v[66:67], v[2:3], v[66:67] op_sel_hi:[0,1]
	v_pk_mul_f32 v[68:69], v[2:3], v[68:69] op_sel_hi:[0,1]
	s_waitcnt vmcnt(0)
	v_pk_mul_f32 v[70:71], v[2:3], v[70:71] op_sel_hi:[0,1]
	v_pk_mul_f32 v[72:73], v[2:3], v[72:73] op_sel_hi:[0,1]
	ds_write2_b32 v22, v40, v41 offset1:1
	ds_write2_b32 v22, v42, v43 offset0:2 offset1:3
	ds_write2_b32 v23, v44, v45 offset1:1
	ds_write2_b32 v24, v46, v47 offset1:1
	ds_write2_b32 v25, v48, v49 offset1:1
	ds_write2_b32 v26, v50, v51 offset1:1
	ds_write2_b32 v27, v54, v55 offset1:1
	ds_write2_b32 v28, v56, v57 offset1:1
	ds_write2_b32 v29, v58, v59 offset1:1
	ds_write2_b32 v30, v60, v61 offset1:1
	ds_write2_b32 v31, v62, v63 offset1:1
	ds_write2_b32 v32, v64, v65 offset1:1
	ds_write2_b32 v33, v66, v67 offset1:1
	ds_write2_b32 v34, v68, v69 offset1:1
	ds_write2_b32 v35, v70, v71 offset1:1
	ds_write2_b32 v37, v72, v73 offset1:1
	s_waitcnt lgkmcnt(0)
	ds_read2_b32 v[44:45], v20 offset0:33 offset1:41
	ds_read2_b32 v[46:47], v20 offset1:8
	ds_read2_b32 v[48:49], v20 offset0:66 offset1:74
	ds_read2_b32 v[50:51], v20 offset0:99 offset1:107
	ds_read2_b32 v[54:55], v20 offset0:132 offset1:140
	ds_read2_b32 v[56:57], v20 offset0:165 offset1:173
	ds_read2_b32 v[58:59], v20 offset0:198 offset1:206
	ds_read2_b32 v[60:61], v20 offset0:231 offset1:239
	s_waitcnt lgkmcnt(6)
	v_cvt_pk_bf16_f32 v40, v46, v44
	s_waitcnt lgkmcnt(4)
	v_cvt_pk_bf16_f32 v41, v48, v50
	s_waitcnt lgkmcnt(2)
	v_cvt_pk_bf16_f32 v42, v54, v56
	v_lshl_add_u64 v[62:63], v[16:17], 0, v[8:9]
	s_waitcnt lgkmcnt(0)
	v_cvt_pk_bf16_f32 v43, v58, v60
	global_store_dwordx4 v[62:63], v[40:43], off sc1
	s_nop 1
	v_cvt_pk_bf16_f32 v40, v47, v45
	v_cvt_pk_bf16_f32 v41, v49, v51
	v_cvt_pk_bf16_f32 v42, v55, v57
	v_cvt_pk_bf16_f32 v43, v59, v61
	ds_read2_b32 v[46:47], v20 offset0:49 offset1:57
	ds_read2_b32 v[48:49], v20 offset0:16 offset1:24
	ds_read2_b32 v[50:51], v20 offset0:82 offset1:90
	ds_read2_b32 v[54:55], v20 offset0:115 offset1:123
	ds_read2_b32 v[56:57], v20 offset0:148 offset1:156
	ds_read2_b32 v[58:59], v20 offset0:181 offset1:189
	ds_read2_b32 v[60:61], v20 offset0:214 offset1:222
	ds_read2_b32 v[62:63], v20 offset0:247 offset1:255
	v_lshl_add_u64 v[44:45], v[16:17], 0, v[10:11]
	global_store_dwordx4 v[44:45], v[40:43], off sc1
	v_lshl_add_u64 v[44:45], v[16:17], 0, v[12:13]
	v_lshl_add_u64 v[16:17], v[16:17], 0, v[14:15]
	s_waitcnt lgkmcnt(6)
	v_cvt_pk_bf16_f32 v40, v48, v46
	s_waitcnt lgkmcnt(4)
	v_cvt_pk_bf16_f32 v41, v50, v54
	s_waitcnt lgkmcnt(2)
	v_cvt_pk_bf16_f32 v42, v56, v58
	s_waitcnt lgkmcnt(0)
	v_cvt_pk_bf16_f32 v43, v60, v62
	global_store_dwordx4 v[44:45], v[40:43], off sc1
	s_nop 1
	v_cvt_pk_bf16_f32 v40, v49, v47
	v_cvt_pk_bf16_f32 v41, v51, v55
	v_cvt_pk_bf16_f32 v42, v57, v59
	v_cvt_pk_bf16_f32 v43, v61, v63
	global_store_dwordx4 v[16:17], v[40:43], off sc1
	s_waitcnt lgkmcnt(0)
	s_branch .LBB0_33

; DI float silu_f(float x) { return x * __builtin_amdgcn_rcpf(1.f + __expf(-x)); }
; DI void phase0(const float* cvec, const float* ada_w, const float* w_in, const float* w_out, bf16* WIN, bf16* WOUT, float* MODP, float* KMAX, bf16* WDT,
;                LAS unsigned char* lds, int tid, int G) {
;     ...
;     for (int task = blockIdx.x; task < 192; task += G) {
;         const int l = task / 96, rem = task % 96, cgp = rem >> 3, ks = rem & 7;
;         const float* W = ada_w + (size_t)l * 1024 * 3072;
;         const int k0 = ks * 128 + wave * 16, col = cgp * 256 + lane * 4;
;         f32x4 acc[8];
; #pragma unroll
;         for (int b = 0; b < 8; ++b) acc[b] = (f32x4){0.f, 0.f, 0.f, 0.f};
; #pragma unroll 4
;         for (int kk = 0; kk < 16; ++kk) { const int k = k0 + kk; const f32x4 w = __builtin_nontemporal_load((const f32x4*)(W + (size_t)k * 3072 + col));
; #pragma unroll
;             for (int b = 0; b < 8; ++b) { const float ca = silu_f(cvec[b * 1024 + k]); acc[b] += w * ca; } }
.LBB0_40:
	s_mul_hi_i32 s8, s20, 0x2aaaaaab
	s_lshr_b32 s9, s8, 31
	s_ashr_i32 s8, s8, 4
	s_add_i32 s9, s8, s9
	s_mul_i32 s8, s9, 0x60
	s_sub_i32 s8, s20, s8
	s_and_b32 s21, s8, 7
	s_lshl_b32 s8, s8, 5
	s_and_b32 s8, s8, 0xffffff00
	v_lshl_add_u32 v0, s21, 7, v53
	v_mad_i64_i32 v[2:3], s[10:11], v0, s12, 0
	v_or_b32_e32 v4, s8, v52
	v_mad_i64_i32 v[2:3], s[10:11], s9, v56, v[2:3]
	v_ashrrev_i32_e32 v5, 31, v4
	v_ashrrev_i32_e32 v1, 31, v0
	v_lshl_add_u64 v[2:3], v[4:5], 2, v[2:3]
	v_lshl_add_u64 v[40:41], s[4:5], 0, v[2:3]
	v_lshl_add_u64 v[42:43], v[0:1], 2, s[38:39]
	s_mov_b64 s[10:11], 0
	v_mov_b32_e32 v0, 0
	v_mov_b32_e32 v1, v39
	v_mov_b32_e32 v2, 0
	v_mov_b32_e32 v3, v39
	v_mov_b32_e32 v28, 0
	v_mov_b32_e32 v29, v39
	v_mov_b32_e32 v30, 0
	v_mov_b32_e32 v31, v39
	v_mov_b32_e32 v4, 0
	v_mov_b32_e32 v5, v39
	v_mov_b32_e32 v6, 0
	v_mov_b32_e32 v7, v39
	v_mov_b32_e32 v8, 0
	v_mov_b32_e32 v9, v39
	v_mov_b32_e32 v10, 0
	v_mov_b32_e32 v11, v39
	v_mov_b32_e32 v12, 0
	v_mov_b32_e32 v13, v39
	v_mov_b32_e32 v14, 0
	v_mov_b32_e32 v15, v39
	v_mov_b32_e32 v16, 0
	v_mov_b32_e32 v17, v39
	v_mov_b32_e32 v18, 0
	v_mov_b32_e32 v19, v39
	v_mov_b32_e32 v20, 0
	v_mov_b32_e32 v21, v39
	v_mov_b32_e32 v22, 0
	v_mov_b32_e32 v23, v39
	v_mov_b32_e32 v24, 0
	v_mov_b32_e32 v25, v39
	v_mov_b32_e32 v26, 0
	v_mov_b32_e32 v27, v39
	v_mbcnt_lo_u32_b32 v44, -1, 0
	v_mbcnt_hi_u32_b32 v44, -1, v44
	v_lshrrev_b32_e32 v45, 4, v44
	v_and_b32_e32 v44, 15, v44
	v_lshl_add_u32 v44, v45, 10, v44
	v_lshlrev_b32_e32 v44, 2, v44
	v_mov_b32_e32 v45, 0
	v_lshl_add_u64 v[44:45], v[42:43], 0, v[44:45]
	v_add_co_u32_e32 v46, vcc, s15, v44
	s_nop 1
	v_addc_co_u32_e32 v47, vcc, 0, v45, vcc
	global_load_dword v48, v[44:45], off
	global_load_dword v49, v[46:47], off
	v_add_co_u32_e32 v50, vcc, s13, v40
	s_nop 1
	v_addc_co_u32_e32 v51, vcc, -1, v41, vcc
	v_add_co_u32_e32 v122, vcc, s18, v40
	s_nop 1
	v_addc_co_u32_e32 v123, vcc, -1, v41, vcc
	v_add_co_u32_e32 v124, vcc, s19, v40
	s_nop 1
	v_addc_co_u32_e32 v125, vcc, -1, v41, vcc
	global_load_dwordx4 v[58:61], v[50:51], off nt
	global_load_dwordx4 v[62:65], v[122:123], off nt
	global_load_dwordx4 v[66:69], v[124:125], off nt
	global_load_dwordx4 v[70:73], v[40:41], off nt
	v_lshl_add_u64 v[50:51], v[50:51], 0, s[6:7]
	v_lshl_add_u64 v[122:123], v[122:123], 0, s[6:7]
	v_lshl_add_u64 v[124:125], v[124:125], 0, s[6:7]
	v_lshl_add_u64 v[40:41], v[40:41], 0, s[6:7]
	global_load_dwordx4 v[74:77], v[50:51], off nt
	global_load_dwordx4 v[78:81], v[122:123], off nt
	global_load_dwordx4 v[82:85], v[124:125], off nt
	global_load_dwordx4 v[86:89], v[40:41], off nt
	v_lshl_add_u64 v[50:51], v[50:51], 0, s[6:7]
	v_lshl_add_u64 v[122:123], v[122:123], 0, s[6:7]
	v_lshl_add_u64 v[124:125], v[124:125], 0, s[6:7]
	v_lshl_add_u64 v[40:41], v[40:41], 0, s[6:7]
	global_load_dwordx4 v[90:93], v[50:51], off nt
	global_load_dwordx4 v[94:97], v[122:123], off nt
	global_load_dwordx4 v[98:101], v[124:125], off nt
	global_load_dwordx4 v[102:105], v[40:41], off nt
	v_lshl_add_u64 v[50:51], v[50:51], 0, s[6:7]
	v_lshl_add_u64 v[122:123], v[122:123], 0, s[6:7]
	v_lshl_add_u64 v[124:125], v[124:125], 0, s[6:7]
	v_lshl_add_u64 v[40:41], v[40:41], 0, s[6:7]
	global_load_dwordx4 v[106:109], v[50:51], off nt
	global_load_dwordx4 v[110:113], v[122:123], off nt
	global_load_dwordx4 v[114:117], v[124:125], off nt
	global_load_dwordx4 v[118:121], v[40:41], off nt
	s_waitcnt vmcnt(16)
	v_mul_f32_e32 v44, 0xbfb8aa3b, v48
	v_mul_f32_e32 v45, 0xbfb8aa3b, v49
	v_exp_f32_e32 v44, v44
	v_exp_f32_e32 v45, v45
	s_nop 0
	v_add_f32_e32 v44, 1.0, v44
	v_add_f32_e32 v45, 1.0, v45
	v_rcp_f32_e32 v44, v44
	v_rcp_f32_e32 v45, v45
	s_nop 0
	v_mul_f32_e32 v48, v48, v44
	v_mul_f32_e32 v49, v49, v45
	s_waitcnt vmcnt(15)
	v_readlane_b32 s22, v48, 0
	v_readlane_b32 s24, v48, 16
	v_readlane_b32 s26, v48, 32
	v_readlane_b32 s28, v48, 48
	v_readlane_b32 s30, v49, 0
	v_readlane_b32 s52, v49, 16
	v_readlane_b32 s54, v49, 32
	v_readlane_b32 s56, v49, 48
	v_pk_fma_f32 v[28:29], v[58:59], s[22:23], v[28:29] op_sel_hi:[1,0,1]
	v_pk_fma_f32 v[30:31], v[60:61], s[22:23], v[30:31] op_sel_hi:[1,0,1]
	v_pk_fma_f32 v[4:5], v[58:59], s[24:25], v[4:5] op_sel_hi:[1,0,1]
	v_pk_fma_f32 v[6:7], v[60:61], s[24:25], v[6:7] op_sel_hi:[1,0,1]
	v_pk_fma_f32 v[8:9], v[58:59], s[26:27], v[8:9] op_sel_hi:[1,0,1]
	v_pk_fma_f32 v[10:11], v[60:61], s[26:27], v[10:11] op_sel_hi:[1,0,1]
	v_pk_fma_f32 v[12:13], v[58:59], s[28:29], v[12:13] op_sel_hi:[1,0,1]
	v_pk_fma_f32 v[14:15], v[60:61], s[28:29], v[14:15] op_sel_hi:[1,0,1]
	v_pk_fma_f32 v[16:17], v[58:59], s[30:31], v[16:17] op_sel_hi:[1,0,1]
	v_pk_fma_f32 v[18:19], v[60:61], s[30:31], v[18:19] op_sel_hi:[1,0,1]
	v_pk_fma_f32 v[20:21], v[58:59], s[52:53], v[20:21] op_sel_hi:[1,0,1]
	v_pk_fma_f32 v[22:23], v[60:61], s[52:53], v[22:23] op_sel_hi:[1,0,1]
	v_pk_fma_f32 v[24:25], v[58:59], s[54:55], v[24:25] op_sel_hi:[1,0,1]
	v_pk_fma_f32 v[26:27], v[60:61], s[54:55], v[26:27] op_sel_hi:[1,0,1]
	v_pk_fma_f32 v[0:1], v[58:59], s[56:57], v[0:1] op_sel_hi:[1,0,1]
	v_pk_fma_f32 v[2:3], v[60:61], s[56:57], v[2:3] op_sel_hi:[1,0,1]
	s_waitcnt vmcnt(14)
; DI float silu_f(float x) { return x * __builtin_amdgcn_rcpf(1.f + __expf(-x)); }
; DI void phase0(const float* cvec, const float* ada_w, const float* w_in, const float* w_out, bf16* WIN, bf16* WOUT, float* MODP, float* KMAX, bf16* WDT,
;                LAS unsigned char* lds, int tid, int G) {
;     ...
; #pragma unroll 4
;         for (int kk = 0; kk < 16; ++kk) { const int k = k0 + kk; const f32x4 w = __builtin_nontemporal_load((const f32x4*)(W + (size_t)k * 3072 + col));
; #pragma unroll
;             for (int b = 0; b < 8; ++b) { const float ca = silu_f(cvec[b * 1024 + k]); acc[b] += w * ca; } }
	v_readlane_b32 s22, v48, 1
	v_readlane_b32 s24, v48, 17
	v_readlane_b32 s26, v48, 33
	v_readlane_b32 s28, v48, 49
	v_readlane_b32 s30, v49, 1
	v_readlane_b32 s52, v49, 17
	v_readlane_b32 s54, v49, 33
	v_readlane_b32 s56, v49, 49
	v_pk_fma_f32 v[28:29], v[62:63], s[22:23], v[28:29] op_sel_hi:[1,0,1]
	v_pk_fma_f32 v[30:31], v[64:65], s[22:23], v[30:31] op_sel_hi:[1,0,1]
	v_pk_fma_f32 v[4:5], v[62:63], s[24:25], v[4:5] op_sel_hi:[1,0,1]
	v_pk_fma_f32 v[6:7], v[64:65], s[24:25], v[6:7] op_sel_hi:[1,0,1]
	v_pk_fma_f32 v[8:9], v[62:63], s[26:27], v[8:9] op_sel_hi:[1,0,1]
	v_pk_fma_f32 v[10:11], v[64:65], s[26:27], v[10:11] op_sel_hi:[1,0,1]
	v_pk_fma_f32 v[12:13], v[62:63], s[28:29], v[12:13] op_sel_hi:[1,0,1]
	v_pk_fma_f32 v[14:15], v[64:65], s[28:29], v[14:15] op_sel_hi:[1,0,1]
	v_pk_fma_f32 v[16:17], v[62:63], s[30:31], v[16:17] op_sel_hi:[1,0,1]
	v_pk_fma_f32 v[18:19], v[64:65], s[30:31], v[18:19] op_sel_hi:[1,0,1]
	v_pk_fma_f32 v[20:21], v[62:63], s[52:53], v[20:21] op_sel_hi:[1,0,1]
	v_pk_fma_f32 v[22:23], v[64:65], s[52:53], v[22:23] op_sel_hi:[1,0,1]
	v_pk_fma_f32 v[24:25], v[62:63], s[54:55], v[24:25] op_sel_hi:[1,0,1]
	v_pk_fma_f32 v[26:27], v[64:65], s[54:55], v[26:27] op_sel_hi:[1,0,1]
	v_pk_fma_f32 v[0:1], v[62:63], s[56:57], v[0:1] op_sel_hi:[1,0,1]
	v_pk_fma_f32 v[2:3], v[64:65], s[56:57], v[2:3] op_sel_hi:[1,0,1]
	s_waitcnt vmcnt(13)
	v_readlane_b32 s22, v48, 2
	v_readlane_b32 s24, v48, 18
	v_readlane_b32 s26, v48, 34
	v_readlane_b32 s28, v48, 50
	v_readlane_b32 s30, v49, 2
	v_readlane_b32 s52, v49, 18
	v_readlane_b32 s54, v49, 34
	v_readlane_b32 s56, v49, 50
	v_pk_fma_f32 v[28:29], v[66:67], s[22:23], v[28:29] op_sel_hi:[1,0,1]
	v_pk_fma_f32 v[30:31], v[68:69], s[22:23], v[30:31] op_sel_hi:[1,0,1]
	v_pk_fma_f32 v[4:5], v[66:67], s[24:25], v[4:5] op_sel_hi:[1,0,1]
	v_pk_fma_f32 v[6:7], v[68:69], s[24:25], v[6:7] op_sel_hi:[1,0,1]
	v_pk_fma_f32 v[8:9], v[66:67], s[26:27], v[8:9] op_sel_hi:[1,0,1]
	v_pk_fma_f32 v[10:11], v[68:69], s[26:27], v[10:11] op_sel_hi:[1,0,1]
	v_pk_fma_f32 v[12:13], v[66:67], s[28:29], v[12:13] op_sel_hi:[1,0,1]
	v_pk_fma_f32 v[14:15], v[68:69], s[28:29], v[14:15] op_sel_hi:[1,0,1]
	v_pk_fma_f32 v[16:17], v[66:67], s[30:31], v[16:17] op_sel_hi:[1,0,1]
	v_pk_fma_f32 v[18:19], v[68:69], s[30:31], v[18:19] op_sel_hi:[1,0,1]
	v_pk_fma_f32 v[20:21], v[66:67], s[52:53], v[20:21] op_sel_hi:[1,0,1]
	v_pk_fma_f32 v[22:23], v[68:69], s[52:53], v[22:23] op_sel_hi:[1,0,1]
	v_pk_fma_f32 v[24:25], v[66:67], s[54:55], v[24:25] op_sel_hi:[1,0,1]
	v_pk_fma_f32 v[26:27], v[68:69], s[54:55], v[26:27] op_sel_hi:[1,0,1]
	v_pk_fma_f32 v[0:1], v[66:67], s[56:57], v[0:1] op_sel_hi:[1,0,1]
	v_pk_fma_f32 v[2:3], v[68:69], s[56:57], v[2:3] op_sel_hi:[1,0,1]
	s_waitcnt vmcnt(12)
	v_readlane_b32 s22, v48, 3
	v_readlane_b32 s24, v48, 19
	v_readlane_b32 s26, v48, 35
	v_readlane_b32 s28, v48, 51
	v_readlane_b32 s30, v49, 3
	v_readlane_b32 s52, v49, 19
	v_readlane_b32 s54, v49, 35
	v_readlane_b32 s56, v49, 51
	v_pk_fma_f32 v[28:29], v[70:71], s[22:23], v[28:29] op_sel_hi:[1,0,1]
	v_pk_fma_f32 v[30:31], v[72:73], s[22:23], v[30:31] op_sel_hi:[1,0,1]
	v_pk_fma_f32 v[4:5], v[70:71], s[24:25], v[4:5] op_sel_hi:[1,0,1]
	v_pk_fma_f32 v[6:7], v[72:73], s[24:25], v[6:7] op_sel_hi:[1,0,1]
	v_pk_fma_f32 v[8:9], v[70:71], s[26:27], v[8:9] op_sel_hi:[1,0,1]
	v_pk_fma_f32 v[10:11], v[72:73], s[26:27], v[10:11] op_sel_hi:[1,0,1]
	v_pk_fma_f32 v[12:13], v[70:71], s[28:29], v[12:13] op_sel_hi:[1,0,1]
	v_pk_fma_f32 v[14:15], v[72:73], s[28:29], v[14:15] op_sel_hi:[1,0,1]
	v_pk_fma_f32 v[16:17], v[70:71], s[30:31], v[16:17] op_sel_hi:[1,0,1]
	v_pk_fma_f32 v[18:19], v[72:73], s[30:31], v[18:19] op_sel_hi:[1,0,1]
	v_pk_fma_f32 v[20:21], v[70:71], s[52:53], v[20:21] op_sel_hi:[1,0,1]
	v_pk_fma_f32 v[22:23], v[72:73], s[52:53], v[22:23] op_sel_hi:[1,0,1]
	v_pk_fma_f32 v[24:25], v[70:71], s[54:55], v[24:25] op_sel_hi:[1,0,1]
	v_pk_fma_f32 v[26:27], v[72:73], s[54:55], v[26:27] op_sel_hi:[1,0,1]
	v_pk_fma_f32 v[0:1], v[70:71], s[56:57], v[0:1] op_sel_hi:[1,0,1]
	v_pk_fma_f32 v[2:3], v[72:73], s[56:57], v[2:3] op_sel_hi:[1,0,1]
	s_waitcnt vmcnt(11)
	v_readlane_b32 s22, v48, 4
	v_readlane_b32 s24, v48, 20
	v_readlane_b32 s26, v48, 36
	v_readlane_b32 s28, v48, 52
	v_readlane_b32 s30, v49, 4
	v_readlane_b32 s52, v49, 20
	v_readlane_b32 s54, v49, 36
	v_readlane_b32 s56, v49, 52
	v_pk_fma_f32 v[28:29], v[74:75], s[22:23], v[28:29] op_sel_hi:[1,0,1]
	v_pk_fma_f32 v[30:31], v[76:77], s[22:23], v[30:31] op_sel_hi:[1,0,1]
	v_pk_fma_f32 v[4:5], v[74:75], s[24:25], v[4:5] op_sel_hi:[1,0,1]
	v_pk_fma_f32 v[6:7], v[76:77], s[24:25], v[6:7] op_sel_hi:[1,0,1]
	v_pk_fma_f32 v[8:9], v[74:75], s[26:27], v[8:9] op_sel_hi:[1,0,1]
	v_pk_fma_f32 v[10:11], v[76:77], s[26:27], v[10:11] op_sel_hi:[1,0,1]
	v_pk_fma_f32 v[12:13], v[74:75], s[28:29], v[12:13] op_sel_hi:[1,0,1]
	v_pk_fma_f32 v[14:15], v[76:77], s[28:29], v[14:15] op_sel_hi:[1,0,1]
	v_pk_fma_f32 v[16:17], v[74:75], s[30:31], v[16:17] op_sel_hi:[1,0,1]
	v_pk_fma_f32 v[18:19], v[76:77], s[30:31], v[18:19] op_sel_hi:[1,0,1]
	v_pk_fma_f32 v[20:21], v[74:75], s[52:53], v[20:21] op_sel_hi:[1,0,1]
	v_pk_fma_f32 v[22:23], v[76:77], s[52:53], v[22:23] op_sel_hi:[1,0,1]
	v_pk_fma_f32 v[24:25], v[74:75], s[54:55], v[24:25] op_sel_hi:[1,0,1]
	v_pk_fma_f32 v[26:27], v[76:77], s[54:55], v[26:27] op_sel_hi:[1,0,1]
	v_pk_fma_f32 v[0:1], v[74:75], s[56:57], v[0:1] op_sel_hi:[1,0,1]
	v_pk_fma_f32 v[2:3], v[76:77], s[56:57], v[2:3] op_sel_hi:[1,0,1]
	s_waitcnt vmcnt(10)
; DI float silu_f(float x) { return x * __builtin_amdgcn_rcpf(1.f + __expf(-x)); }
; DI void phase0(const float* cvec, const float* ada_w, const float* w_in, const float* w_out, bf16* WIN, bf16* WOUT, float* MODP, float* KMAX, bf16* WDT,
;                LAS unsigned char* lds, int tid, int G) {
;     ...
; #pragma unroll 4
;         for (int kk = 0; kk < 16; ++kk) { const int k = k0 + kk; const f32x4 w = __builtin_nontemporal_load((const f32x4*)(W + (size_t)k * 3072 + col));
; #pragma unroll
;             for (int b = 0; b < 8; ++b) { const float ca = silu_f(cvec[b * 1024 + k]); acc[b] += w * ca; } }
	v_readlane_b32 s22, v48, 5
	v_readlane_b32 s24, v48, 21
	v_readlane_b32 s26, v48, 37
	v_readlane_b32 s28, v48, 53
	v_readlane_b32 s30, v49, 5
	v_readlane_b32 s52, v49, 21
	v_readlane_b32 s54, v49, 37
	v_readlane_b32 s56, v49, 53
	v_pk_fma_f32 v[28:29], v[78:79], s[22:23], v[28:29] op_sel_hi:[1,0,1]
	v_pk_fma_f32 v[30:31], v[80:81], s[22:23], v[30:31] op_sel_hi:[1,0,1]
	v_pk_fma_f32 v[4:5], v[78:79], s[24:25], v[4:5] op_sel_hi:[1,0,1]
	v_pk_fma_f32 v[6:7], v[80:81], s[24:25], v[6:7] op_sel_hi:[1,0,1]
	v_pk_fma_f32 v[8:9], v[78:79], s[26:27], v[8:9] op_sel_hi:[1,0,1]
	v_pk_fma_f32 v[10:11], v[80:81], s[26:27], v[10:11] op_sel_hi:[1,0,1]
	v_pk_fma_f32 v[12:13], v[78:79], s[28:29], v[12:13] op_sel_hi:[1,0,1]
	v_pk_fma_f32 v[14:15], v[80:81], s[28:29], v[14:15] op_sel_hi:[1,0,1]
	v_pk_fma_f32 v[16:17], v[78:79], s[30:31], v[16:17] op_sel_hi:[1,0,1]
	v_pk_fma_f32 v[18:19], v[80:81], s[30:31], v[18:19] op_sel_hi:[1,0,1]
	v_pk_fma_f32 v[20:21], v[78:79], s[52:53], v[20:21] op_sel_hi:[1,0,1]
	v_pk_fma_f32 v[22:23], v[80:81], s[52:53], v[22:23] op_sel_hi:[1,0,1]
	v_pk_fma_f32 v[24:25], v[78:79], s[54:55], v[24:25] op_sel_hi:[1,0,1]
	v_pk_fma_f32 v[26:27], v[80:81], s[54:55], v[26:27] op_sel_hi:[1,0,1]
	v_pk_fma_f32 v[0:1], v[78:79], s[56:57], v[0:1] op_sel_hi:[1,0,1]
	v_pk_fma_f32 v[2:3], v[80:81], s[56:57], v[2:3] op_sel_hi:[1,0,1]
	s_waitcnt vmcnt(9)
	v_readlane_b32 s22, v48, 6
	v_readlane_b32 s24, v48, 22
	v_readlane_b32 s26, v48, 38
	v_readlane_b32 s28, v48, 54
	v_readlane_b32 s30, v49, 6
	v_readlane_b32 s52, v49, 22
	v_readlane_b32 s54, v49, 38
	v_readlane_b32 s56, v49, 54
	v_pk_fma_f32 v[28:29], v[82:83], s[22:23], v[28:29] op_sel_hi:[1,0,1]
	v_pk_fma_f32 v[30:31], v[84:85], s[22:23], v[30:31] op_sel_hi:[1,0,1]
	v_pk_fma_f32 v[4:5], v[82:83], s[24:25], v[4:5] op_sel_hi:[1,0,1]
	v_pk_fma_f32 v[6:7], v[84:85], s[24:25], v[6:7] op_sel_hi:[1,0,1]
	v_pk_fma_f32 v[8:9], v[82:83], s[26:27], v[8:9] op_sel_hi:[1,0,1]
	v_pk_fma_f32 v[10:11], v[84:85], s[26:27], v[10:11] op_sel_hi:[1,0,1]
	v_pk_fma_f32 v[12:13], v[82:83], s[28:29], v[12:13] op_sel_hi:[1,0,1]
	v_pk_fma_f32 v[14:15], v[84:85], s[28:29], v[14:15] op_sel_hi:[1,0,1]
	v_pk_fma_f32 v[16:17], v[82:83], s[30:31], v[16:17] op_sel_hi:[1,0,1]
	v_pk_fma_f32 v[18:19], v[84:85], s[30:31], v[18:19] op_sel_hi:[1,0,1]
	v_pk_fma_f32 v[20:21], v[82:83], s[52:53], v[20:21] op_sel_hi:[1,0,1]
	v_pk_fma_f32 v[22:23], v[84:85], s[52:53], v[22:23] op_sel_hi:[1,0,1]
	v_pk_fma_f32 v[24:25], v[82:83], s[54:55], v[24:25] op_sel_hi:[1,0,1]
	v_pk_fma_f32 v[26:27], v[84:85], s[54:55], v[26:27] op_sel_hi:[1,0,1]
	v_pk_fma_f32 v[0:1], v[82:83], s[56:57], v[0:1] op_sel_hi:[1,0,1]
	v_pk_fma_f32 v[2:3], v[84:85], s[56:57], v[2:3] op_sel_hi:[1,0,1]
	s_waitcnt vmcnt(8)
	v_readlane_b32 s22, v48, 7
	v_readlane_b32 s24, v48, 23
	v_readlane_b32 s26, v48, 39
	v_readlane_b32 s28, v48, 55
	v_readlane_b32 s30, v49, 7
	v_readlane_b32 s52, v49, 23
	v_readlane_b32 s54, v49, 39
	v_readlane_b32 s56, v49, 55
	v_pk_fma_f32 v[28:29], v[86:87], s[22:23], v[28:29] op_sel_hi:[1,0,1]
	v_pk_fma_f32 v[30:31], v[88:89], s[22:23], v[30:31] op_sel_hi:[1,0,1]
	v_pk_fma_f32 v[4:5], v[86:87], s[24:25], v[4:5] op_sel_hi:[1,0,1]
	v_pk_fma_f32 v[6:7], v[88:89], s[24:25], v[6:7] op_sel_hi:[1,0,1]
	v_pk_fma_f32 v[8:9], v[86:87], s[26:27], v[8:9] op_sel_hi:[1,0,1]
	v_pk_fma_f32 v[10:11], v[88:89], s[26:27], v[10:11] op_sel_hi:[1,0,1]
	v_pk_fma_f32 v[12:13], v[86:87], s[28:29], v[12:13] op_sel_hi:[1,0,1]
	v_pk_fma_f32 v[14:15], v[88:89], s[28:29], v[14:15] op_sel_hi:[1,0,1]
	v_pk_fma_f32 v[16:17], v[86:87], s[30:31], v[16:17] op_sel_hi:[1,0,1]
	v_pk_fma_f32 v[18:19], v[88:89], s[30:31], v[18:19] op_sel_hi:[1,0,1]
	v_pk_fma_f32 v[20:21], v[86:87], s[52:53], v[20:21] op_sel_hi:[1,0,1]
	v_pk_fma_f32 v[22:23], v[88:89], s[52:53], v[22:23] op_sel_hi:[1,0,1]
	v_pk_fma_f32 v[24:25], v[86:87], s[54:55], v[24:25] op_sel_hi:[1,0,1]
	v_pk_fma_f32 v[26:27], v[88:89], s[54:55], v[26:27] op_sel_hi:[1,0,1]
	v_pk_fma_f32 v[0:1], v[86:87], s[56:57], v[0:1] op_sel_hi:[1,0,1]
	v_pk_fma_f32 v[2:3], v[88:89], s[56:57], v[2:3] op_sel_hi:[1,0,1]
	s_waitcnt vmcnt(7)
	v_readlane_b32 s22, v48, 8
	v_readlane_b32 s24, v48, 24
	v_readlane_b32 s26, v48, 40
	v_readlane_b32 s28, v48, 56
	v_readlane_b32 s30, v49, 8
	v_readlane_b32 s52, v49, 24
	v_readlane_b32 s54, v49, 40
	v_readlane_b32 s56, v49, 56
	v_pk_fma_f32 v[28:29], v[90:91], s[22:23], v[28:29] op_sel_hi:[1,0,1]
	v_pk_fma_f32 v[30:31], v[92:93], s[22:23], v[30:31] op_sel_hi:[1,0,1]
	v_pk_fma_f32 v[4:5], v[90:91], s[24:25], v[4:5] op_sel_hi:[1,0,1]
	v_pk_fma_f32 v[6:7], v[92:93], s[24:25], v[6:7] op_sel_hi:[1,0,1]
	v_pk_fma_f32 v[8:9], v[90:91], s[26:27], v[8:9] op_sel_hi:[1,0,1]
	v_pk_fma_f32 v[10:11], v[92:93], s[26:27], v[10:11] op_sel_hi:[1,0,1]
	v_pk_fma_f32 v[12:13], v[90:91], s[28:29], v[12:13] op_sel_hi:[1,0,1]
	v_pk_fma_f32 v[14:15], v[92:93], s[28:29], v[14:15] op_sel_hi:[1,0,1]
	v_pk_fma_f32 v[16:17], v[90:91], s[30:31], v[16:17] op_sel_hi:[1,0,1]
	v_pk_fma_f32 v[18:19], v[92:93], s[30:31], v[18:19] op_sel_hi:[1,0,1]
	v_pk_fma_f32 v[20:21], v[90:91], s[52:53], v[20:21] op_sel_hi:[1,0,1]
	v_pk_fma_f32 v[22:23], v[92:93], s[52:53], v[22:23] op_sel_hi:[1,0,1]
	v_pk_fma_f32 v[24:25], v[90:91], s[54:55], v[24:25] op_sel_hi:[1,0,1]
	v_pk_fma_f32 v[26:27], v[92:93], s[54:55], v[26:27] op_sel_hi:[1,0,1]
	v_pk_fma_f32 v[0:1], v[90:91], s[56:57], v[0:1] op_sel_hi:[1,0,1]
	v_pk_fma_f32 v[2:3], v[92:93], s[56:57], v[2:3] op_sel_hi:[1,0,1]
	s_waitcnt vmcnt(6)
; DI float silu_f(float x) { return x * __builtin_amdgcn_rcpf(1.f + __expf(-x)); }
; DI void phase0(const float* cvec, const float* ada_w, const float* w_in, const float* w_out, bf16* WIN, bf16* WOUT, float* MODP, float* KMAX, bf16* WDT,
;                LAS unsigned char* lds, int tid, int G) {
;     ...
; #pragma unroll 4
;         for (int kk = 0; kk < 16; ++kk) { const int k = k0 + kk; const f32x4 w = __builtin_nontemporal_load((const f32x4*)(W + (size_t)k * 3072 + col));
; #pragma unroll
;             for (int b = 0; b < 8; ++b) { const float ca = silu_f(cvec[b * 1024 + k]); acc[b] += w * ca; } }
	v_readlane_b32 s22, v48, 9
	v_readlane_b32 s24, v48, 25
	v_readlane_b32 s26, v48, 41
	v_readlane_b32 s28, v48, 57
	v_readlane_b32 s30, v49, 9
	v_readlane_b32 s52, v49, 25
	v_readlane_b32 s54, v49, 41
	v_readlane_b32 s56, v49, 57
	v_pk_fma_f32 v[28:29], v[94:95], s[22:23], v[28:29] op_sel_hi:[1,0,1]
	v_pk_fma_f32 v[30:31], v[96:97], s[22:23], v[30:31] op_sel_hi:[1,0,1]
	v_pk_fma_f32 v[4:5], v[94:95], s[24:25], v[4:5] op_sel_hi:[1,0,1]
	v_pk_fma_f32 v[6:7], v[96:97], s[24:25], v[6:7] op_sel_hi:[1,0,1]
	v_pk_fma_f32 v[8:9], v[94:95], s[26:27], v[8:9] op_sel_hi:[1,0,1]
	v_pk_fma_f32 v[10:11], v[96:97], s[26:27], v[10:11] op_sel_hi:[1,0,1]
	v_pk_fma_f32 v[12:13], v[94:95], s[28:29], v[12:13] op_sel_hi:[1,0,1]
	v_pk_fma_f32 v[14:15], v[96:97], s[28:29], v[14:15] op_sel_hi:[1,0,1]
	v_pk_fma_f32 v[16:17], v[94:95], s[30:31], v[16:17] op_sel_hi:[1,0,1]
	v_pk_fma_f32 v[18:19], v[96:97], s[30:31], v[18:19] op_sel_hi:[1,0,1]
	v_pk_fma_f32 v[20:21], v[94:95], s[52:53], v[20:21] op_sel_hi:[1,0,1]
	v_pk_fma_f32 v[22:23], v[96:97], s[52:53], v[22:23] op_sel_hi:[1,0,1]
	v_pk_fma_f32 v[24:25], v[94:95], s[54:55], v[24:25] op_sel_hi:[1,0,1]
	v_pk_fma_f32 v[26:27], v[96:97], s[54:55], v[26:27] op_sel_hi:[1,0,1]
	v_pk_fma_f32 v[0:1], v[94:95], s[56:57], v[0:1] op_sel_hi:[1,0,1]
	v_pk_fma_f32 v[2:3], v[96:97], s[56:57], v[2:3] op_sel_hi:[1,0,1]
	s_waitcnt vmcnt(5)
	v_readlane_b32 s22, v48, 10
	v_readlane_b32 s24, v48, 26
	v_readlane_b32 s26, v48, 42
	v_readlane_b32 s28, v48, 58
	v_readlane_b32 s30, v49, 10
	v_readlane_b32 s52, v49, 26
	v_readlane_b32 s54, v49, 42
	v_readlane_b32 s56, v49, 58
	v_pk_fma_f32 v[28:29], v[98:99], s[22:23], v[28:29] op_sel_hi:[1,0,1]
	v_pk_fma_f32 v[30:31], v[100:101], s[22:23], v[30:31] op_sel_hi:[1,0,1]
	v_pk_fma_f32 v[4:5], v[98:99], s[24:25], v[4:5] op_sel_hi:[1,0,1]
	v_pk_fma_f32 v[6:7], v[100:101], s[24:25], v[6:7] op_sel_hi:[1,0,1]
	v_pk_fma_f32 v[8:9], v[98:99], s[26:27], v[8:9] op_sel_hi:[1,0,1]
	v_pk_fma_f32 v[10:11], v[100:101], s[26:27], v[10:11] op_sel_hi:[1,0,1]
	v_pk_fma_f32 v[12:13], v[98:99], s[28:29], v[12:13] op_sel_hi:[1,0,1]
	v_pk_fma_f32 v[14:15], v[100:101], s[28:29], v[14:15] op_sel_hi:[1,0,1]
	v_pk_fma_f32 v[16:17], v[98:99], s[30:31], v[16:17] op_sel_hi:[1,0,1]
	v_pk_fma_f32 v[18:19], v[100:101], s[30:31], v[18:19] op_sel_hi:[1,0,1]
	v_pk_fma_f32 v[20:21], v[98:99], s[52:53], v[20:21] op_sel_hi:[1,0,1]
	v_pk_fma_f32 v[22:23], v[100:101], s[52:53], v[22:23] op_sel_hi:[1,0,1]
	v_pk_fma_f32 v[24:25], v[98:99], s[54:55], v[24:25] op_sel_hi:[1,0,1]
	v_pk_fma_f32 v[26:27], v[100:101], s[54:55], v[26:27] op_sel_hi:[1,0,1]
	v_pk_fma_f32 v[0:1], v[98:99], s[56:57], v[0:1] op_sel_hi:[1,0,1]
	v_pk_fma_f32 v[2:3], v[100:101], s[56:57], v[2:3] op_sel_hi:[1,0,1]
	s_waitcnt vmcnt(4)
	v_readlane_b32 s22, v48, 11
	v_readlane_b32 s24, v48, 27
	v_readlane_b32 s26, v48, 43
	v_readlane_b32 s28, v48, 59
	v_readlane_b32 s30, v49, 11
	v_readlane_b32 s52, v49, 27
	v_readlane_b32 s54, v49, 43
	v_readlane_b32 s56, v49, 59
	v_pk_fma_f32 v[28:29], v[102:103], s[22:23], v[28:29] op_sel_hi:[1,0,1]
	v_pk_fma_f32 v[30:31], v[104:105], s[22:23], v[30:31] op_sel_hi:[1,0,1]
	v_pk_fma_f32 v[4:5], v[102:103], s[24:25], v[4:5] op_sel_hi:[1,0,1]
	v_pk_fma_f32 v[6:7], v[104:105], s[24:25], v[6:7] op_sel_hi:[1,0,1]
	v_pk_fma_f32 v[8:9], v[102:103], s[26:27], v[8:9] op_sel_hi:[1,0,1]
	v_pk_fma_f32 v[10:11], v[104:105], s[26:27], v[10:11] op_sel_hi:[1,0,1]
	v_pk_fma_f32 v[12:13], v[102:103], s[28:29], v[12:13] op_sel_hi:[1,0,1]
	v_pk_fma_f32 v[14:15], v[104:105], s[28:29], v[14:15] op_sel_hi:[1,0,1]
	v_pk_fma_f32 v[16:17], v[102:103], s[30:31], v[16:17] op_sel_hi:[1,0,1]
	v_pk_fma_f32 v[18:19], v[104:105], s[30:31], v[18:19] op_sel_hi:[1,0,1]
	v_pk_fma_f32 v[20:21], v[102:103], s[52:53], v[20:21] op_sel_hi:[1,0,1]
	v_pk_fma_f32 v[22:23], v[104:105], s[52:53], v[22:23] op_sel_hi:[1,0,1]
	v_pk_fma_f32 v[24:25], v[102:103], s[54:55], v[24:25] op_sel_hi:[1,0,1]
	v_pk_fma_f32 v[26:27], v[104:105], s[54:55], v[26:27] op_sel_hi:[1,0,1]
	v_pk_fma_f32 v[0:1], v[102:103], s[56:57], v[0:1] op_sel_hi:[1,0,1]
	v_pk_fma_f32 v[2:3], v[104:105], s[56:57], v[2:3] op_sel_hi:[1,0,1]
	s_waitcnt vmcnt(3)
	v_readlane_b32 s22, v48, 12
	v_readlane_b32 s24, v48, 28
	v_readlane_b32 s26, v48, 44
	v_readlane_b32 s28, v48, 60
	v_readlane_b32 s30, v49, 12
	v_readlane_b32 s52, v49, 28
	v_readlane_b32 s54, v49, 44
	v_readlane_b32 s56, v49, 60
	v_pk_fma_f32 v[28:29], v[106:107], s[22:23], v[28:29] op_sel_hi:[1,0,1]
	v_pk_fma_f32 v[30:31], v[108:109], s[22:23], v[30:31] op_sel_hi:[1,0,1]
	v_pk_fma_f32 v[4:5], v[106:107], s[24:25], v[4:5] op_sel_hi:[1,0,1]
	v_pk_fma_f32 v[6:7], v[108:109], s[24:25], v[6:7] op_sel_hi:[1,0,1]
	v_pk_fma_f32 v[8:9], v[106:107], s[26:27], v[8:9] op_sel_hi:[1,0,1]
	v_pk_fma_f32 v[10:11], v[108:109], s[26:27], v[10:11] op_sel_hi:[1,0,1]
	v_pk_fma_f32 v[12:13], v[106:107], s[28:29], v[12:13] op_sel_hi:[1,0,1]
	v_pk_fma_f32 v[14:15], v[108:109], s[28:29], v[14:15] op_sel_hi:[1,0,1]
	v_pk_fma_f32 v[16:17], v[106:107], s[30:31], v[16:17] op_sel_hi:[1,0,1]
	v_pk_fma_f32 v[18:19], v[108:109], s[30:31], v[18:19] op_sel_hi:[1,0,1]
	v_pk_fma_f32 v[20:21], v[106:107], s[52:53], v[20:21] op_sel_hi:[1,0,1]
	v_pk_fma_f32 v[22:23], v[108:109], s[52:53], v[22:23] op_sel_hi:[1,0,1]
	v_pk_fma_f32 v[24:25], v[106:107], s[54:55], v[24:25] op_sel_hi:[1,0,1]
	v_pk_fma_f32 v[26:27], v[108:109], s[54:55], v[26:27] op_sel_hi:[1,0,1]
	v_pk_fma_f32 v[0:1], v[106:107], s[56:57], v[0:1] op_sel_hi:[1,0,1]
	v_pk_fma_f32 v[2:3], v[108:109], s[56:57], v[2:3] op_sel_hi:[1,0,1]
	s_waitcnt vmcnt(2)
; #define LAS __attribute__((address_space(3)))
; DI float silu_f(float x) { return x * __builtin_amdgcn_rcpf(1.f + __expf(-x)); }
; DI void phase0(const float* cvec, const float* ada_w, const float* w_in, const float* w_out, bf16* WIN, bf16* WOUT, float* MODP, float* KMAX, bf16* WDT,
;                LAS unsigned char* lds, int tid, int G) {
;     ...
;         for (int kk = 0; kk < 16; ++kk) { const int k = k0 + kk; const f32x4 w = __builtin_nontemporal_load((const f32x4*)(W + (size_t)k * 3072 + col));
; #pragma unroll
;             for (int b = 0; b < 8; ++b) { const float ca = silu_f(cvec[b * 1024 + k]); acc[b] += w * ca; } }
;         LAS float* red = (LAS float*)lds;
; #pragma unroll
;         for (int b = 0; b < 8; ++b) *(LAS f32x4*)(red + (wave * 8 + b) * 256 + lane * 4) = acc[b];
;         __syncthreads();
;         { const int idx = tid * 4, b = idx >> 8, cc = idx & 255; f32x4 s = (f32x4){0.f, 0.f, 0.f, 0.f};
; #pragma unroll
;           for (int w = 0; w < 8; ++w) s += *(const LAS f32x4*)(red + (w * 8 + b) * 256 + cc);
;           *(f32x4*)(MODP + ((size_t)(l * 8 + ks) * 8 + b) * 3072 + cgp * 256 + cc) = s; }
;         __syncthreads();
	v_readlane_b32 s22, v48, 13
	v_readlane_b32 s24, v48, 29
	v_readlane_b32 s26, v48, 45
	v_readlane_b32 s28, v48, 61
	v_readlane_b32 s30, v49, 13
	v_readlane_b32 s52, v49, 29
	v_readlane_b32 s54, v49, 45
	v_readlane_b32 s56, v49, 61
	v_pk_fma_f32 v[28:29], v[110:111], s[22:23], v[28:29] op_sel_hi:[1,0,1]
	v_pk_fma_f32 v[30:31], v[112:113], s[22:23], v[30:31] op_sel_hi:[1,0,1]
	v_pk_fma_f32 v[4:5], v[110:111], s[24:25], v[4:5] op_sel_hi:[1,0,1]
	v_pk_fma_f32 v[6:7], v[112:113], s[24:25], v[6:7] op_sel_hi:[1,0,1]
	v_pk_fma_f32 v[8:9], v[110:111], s[26:27], v[8:9] op_sel_hi:[1,0,1]
	v_pk_fma_f32 v[10:11], v[112:113], s[26:27], v[10:11] op_sel_hi:[1,0,1]
	v_pk_fma_f32 v[12:13], v[110:111], s[28:29], v[12:13] op_sel_hi:[1,0,1]
	v_pk_fma_f32 v[14:15], v[112:113], s[28:29], v[14:15] op_sel_hi:[1,0,1]
	v_pk_fma_f32 v[16:17], v[110:111], s[30:31], v[16:17] op_sel_hi:[1,0,1]
	v_pk_fma_f32 v[18:19], v[112:113], s[30:31], v[18:19] op_sel_hi:[1,0,1]
	v_pk_fma_f32 v[20:21], v[110:111], s[52:53], v[20:21] op_sel_hi:[1,0,1]
	v_pk_fma_f32 v[22:23], v[112:113], s[52:53], v[22:23] op_sel_hi:[1,0,1]
	v_pk_fma_f32 v[24:25], v[110:111], s[54:55], v[24:25] op_sel_hi:[1,0,1]
	v_pk_fma_f32 v[26:27], v[112:113], s[54:55], v[26:27] op_sel_hi:[1,0,1]
	v_pk_fma_f32 v[0:1], v[110:111], s[56:57], v[0:1] op_sel_hi:[1,0,1]
	v_pk_fma_f32 v[2:3], v[112:113], s[56:57], v[2:3] op_sel_hi:[1,0,1]
	s_waitcnt vmcnt(1)
	v_readlane_b32 s22, v48, 14
	v_readlane_b32 s24, v48, 30
	v_readlane_b32 s26, v48, 46
	v_readlane_b32 s28, v48, 62
	v_readlane_b32 s30, v49, 14
	v_readlane_b32 s52, v49, 30
	v_readlane_b32 s54, v49, 46
	v_readlane_b32 s56, v49, 62
	v_pk_fma_f32 v[28:29], v[114:115], s[22:23], v[28:29] op_sel_hi:[1,0,1]
	v_pk_fma_f32 v[30:31], v[116:117], s[22:23], v[30:31] op_sel_hi:[1,0,1]
	v_pk_fma_f32 v[4:5], v[114:115], s[24:25], v[4:5] op_sel_hi:[1,0,1]
	v_pk_fma_f32 v[6:7], v[116:117], s[24:25], v[6:7] op_sel_hi:[1,0,1]
	v_pk_fma_f32 v[8:9], v[114:115], s[26:27], v[8:9] op_sel_hi:[1,0,1]
	v_pk_fma_f32 v[10:11], v[116:117], s[26:27], v[10:11] op_sel_hi:[1,0,1]
	v_pk_fma_f32 v[12:13], v[114:115], s[28:29], v[12:13] op_sel_hi:[1,0,1]
	v_pk_fma_f32 v[14:15], v[116:117], s[28:29], v[14:15] op_sel_hi:[1,0,1]
	v_pk_fma_f32 v[16:17], v[114:115], s[30:31], v[16:17] op_sel_hi:[1,0,1]
	v_pk_fma_f32 v[18:19], v[116:117], s[30:31], v[18:19] op_sel_hi:[1,0,1]
	v_pk_fma_f32 v[20:21], v[114:115], s[52:53], v[20:21] op_sel_hi:[1,0,1]
	v_pk_fma_f32 v[22:23], v[116:117], s[52:53], v[22:23] op_sel_hi:[1,0,1]
	v_pk_fma_f32 v[24:25], v[114:115], s[54:55], v[24:25] op_sel_hi:[1,0,1]
	v_pk_fma_f32 v[26:27], v[116:117], s[54:55], v[26:27] op_sel_hi:[1,0,1]
	v_pk_fma_f32 v[0:1], v[114:115], s[56:57], v[0:1] op_sel_hi:[1,0,1]
	v_pk_fma_f32 v[2:3], v[116:117], s[56:57], v[2:3] op_sel_hi:[1,0,1]
	s_waitcnt vmcnt(0)
	v_readlane_b32 s22, v48, 15
	v_readlane_b32 s24, v48, 31
	v_readlane_b32 s26, v48, 47
	v_readlane_b32 s28, v48, 63
	v_readlane_b32 s30, v49, 15
	v_readlane_b32 s52, v49, 31
	v_readlane_b32 s54, v49, 47
	v_readlane_b32 s56, v49, 63
	v_pk_fma_f32 v[28:29], v[118:119], s[22:23], v[28:29] op_sel_hi:[1,0,1]
	v_pk_fma_f32 v[30:31], v[120:121], s[22:23], v[30:31] op_sel_hi:[1,0,1]
	v_pk_fma_f32 v[4:5], v[118:119], s[24:25], v[4:5] op_sel_hi:[1,0,1]
	v_pk_fma_f32 v[6:7], v[120:121], s[24:25], v[6:7] op_sel_hi:[1,0,1]
	v_pk_fma_f32 v[8:9], v[118:119], s[26:27], v[8:9] op_sel_hi:[1,0,1]
	v_pk_fma_f32 v[10:11], v[120:121], s[26:27], v[10:11] op_sel_hi:[1,0,1]
	v_pk_fma_f32 v[12:13], v[118:119], s[28:29], v[12:13] op_sel_hi:[1,0,1]
	v_pk_fma_f32 v[14:15], v[120:121], s[28:29], v[14:15] op_sel_hi:[1,0,1]
	v_pk_fma_f32 v[16:17], v[118:119], s[30:31], v[16:17] op_sel_hi:[1,0,1]
	v_pk_fma_f32 v[18:19], v[120:121], s[30:31], v[18:19] op_sel_hi:[1,0,1]
	v_pk_fma_f32 v[20:21], v[118:119], s[52:53], v[20:21] op_sel_hi:[1,0,1]
	v_pk_fma_f32 v[22:23], v[120:121], s[52:53], v[22:23] op_sel_hi:[1,0,1]
	v_pk_fma_f32 v[24:25], v[118:119], s[54:55], v[24:25] op_sel_hi:[1,0,1]
	v_pk_fma_f32 v[26:27], v[120:121], s[54:55], v[26:27] op_sel_hi:[1,0,1]
	v_pk_fma_f32 v[0:1], v[118:119], s[56:57], v[0:1] op_sel_hi:[1,0,1]
	v_pk_fma_f32 v[2:3], v[120:121], s[56:57], v[2:3] op_sel_hi:[1,0,1]
	ds_write_b128 v54, v[28:31]
	ds_write_b128 v54, v[4:7] offset:1024
	ds_write_b128 v54, v[8:11] offset:2048
	ds_write_b128 v54, v[12:15] offset:3072
	ds_write_b128 v54, v[16:19] offset:4096
	ds_write_b128 v54, v[20:23] offset:5120
	ds_write_b128 v54, v[24:27] offset:6144
	ds_write_b128 v54, v[0:3] offset:7168
	s_waitcnt lgkmcnt(0)
	s_barrier
	ds_read_b128 v[0:3], v55
	ds_read_b128 v[4:7], v55 offset:8192
	ds_read_b128 v[8:11], v55 offset:16384
	s_lshl_b32 s9, s9, 3
	s_or_b32 s10, s9, s21
	s_waitcnt lgkmcnt(2)
	v_pk_add_f32 v[2:3], v[2:3], 0 op_sel_hi:[1,0]
	v_pk_add_f32 v[12:13], v[0:1], 0 op_sel_hi:[1,0]
	s_waitcnt lgkmcnt(1)
	v_pk_add_f32 v[6:7], v[2:3], v[6:7]
	ds_read_b128 v[0:3], v55 offset:24576
	v_pk_add_f32 v[12:13], v[12:13], v[4:5]
	s_waitcnt lgkmcnt(1)
	v_pk_add_f32 v[10:11], v[6:7], v[10:11]
	ds_read_b128 v[4:7], v55 offset:32768
	v_pk_add_f32 v[8:9], v[12:13], v[8:9]
	s_waitcnt lgkmcnt(1)
	v_pk_add_f32 v[10:11], v[10:11], v[2:3]
	v_pk_add_f32 v[12:13], v[8:9], v[0:1]
	ds_read_b128 v[0:3], v55 offset:40960
	s_waitcnt lgkmcnt(1)
	v_pk_add_f32 v[14:15], v[10:11], v[6:7]
	ds_read_b128 v[6:9], v55 offset:49152
	v_pk_add_f32 v[4:5], v[12:13], v[4:5]
	ds_read_b128 v[10:13], v55 offset:57344
	s_waitcnt lgkmcnt(2)
	v_pk_add_f32 v[0:1], v[4:5], v[0:1]
	s_ashr_i32 s11, s10, 31
	s_waitcnt lgkmcnt(1)
	v_pk_add_f32 v[0:1], v[0:1], v[6:7]
	v_lshl_add_u64 v[4:5], s[10:11], 3, v[36:37]
	v_mov_b64_e32 v[6:7], s[58:59]
	v_mad_u64_u32 v[6:7], s[10:11], v4, s12, v[6:7]
	v_pk_add_f32 v[2:3], v[14:15], v[2:3]
	v_mad_i32_i24 v7, v5, s12, v7
	s_ashr_i32 s9, s8, 31
	v_pk_add_f32 v[2:3], v[2:3], v[8:9]
	v_lshl_add_u64 v[4:5], s[8:9], 2, v[6:7]
	s_add_i32 s20, s20, s88
	s_waitcnt lgkmcnt(0)
	v_pk_add_f32 v[2:3], v[2:3], v[12:13]
	v_pk_add_f32 v[0:1], v[0:1], v[10:11]
	v_lshl_add_u64 v[4:5], v[4:5], 0, v[38:39]
	s_cmpk_gt_i32 s20, 0xbf
	global_store_dwordx4 v[4:5], v[0:3], off sc1
	s_barrier
	s_cbranch_scc0 .LBB0_40

; __device__ __forceinline__ unsigned xb_ld(unsigned* p)              { return __hip_atomic_load(p, __ATOMIC_RELAXED, __HIP_MEMORY_SCOPE_AGENT); }
; __device__ __forceinline__ unsigned xb_add(unsigned* p, unsigned v) { return __hip_atomic_fetch_add(p, v, __ATOMIC_RELAXED, __HIP_MEMORY_SCOPE_AGENT); }
; #define XB_SPIN(cond, bar) do { unsigned _sp = 0; while (cond) { __builtin_amdgcn_s_sleep(1); \
;     if ((++_sp & 255u) == 0u) { if (xb_ld(&(bar)[XB_TMO])) break; if (_sp > XB_SPIN_CAP) { atomicAdd(&(bar)[XB_TMO], 1u); break; } } } } while (0)
; __device__ __forceinline__ void xcd_barrier(const XcdBarrier& b) {
;     ...
;     if (threadIdx.x == 0) {
;         unsigned* bar = b.bar;
;         __builtin_amdgcn_s_waitcnt(0);
;         unsigned nloc = b.st[0], nx = b.st[1];
;         if (nloc == 0u) { xcd_barrier_complete(bar, b.x, nloc, nx); b.st[0] = nloc; b.st[1] = nx; }
;         const unsigned old = xb_add(&bar[XB_XSUB(b.x)], 1u);
;         const unsigned gen = old / nloc;
;         if (old + 1u == (gen + 1u) * nloc) {
;             __builtin_amdgcn_fence(__ATOMIC_RELEASE, "agent");
;             asm volatile("s_waitcnt vmcnt(0)" ::: "memory");
;             const unsigned og = xb_add(&bar[XB_TOP], 1u);
;             const unsigned tg = og / nx;
;             if (og + 1u == (tg + 1u) * nx) xb_add(&bar[XB_TOPGEN], 1u);
;             else XB_SPIN(xb_ld(&bar[XB_TOPGEN]) == tg, bar);
;             __builtin_amdgcn_fence(__ATOMIC_ACQUIRE, "agent");
;             xb_add(&bar[XB_XGEN(b.x)], 1u);
;             asm volatile("s_waitcnt vmcnt(0)" ::: "memory");
;         } else {
;             XB_SPIN(xb_ld(&bar[XB_XGEN(b.x)]) == gen, bar);
.LBB0_59:
	s_lshl_b32 s0, s33, 8
	s_add_u32 s23, s36, s0
	s_addc_u32 s22, s37, 0
	v_mov_b32_e32 v1, s23
	v_add_co_u32_e32 v4, vcc, 0x1000, v1
	v_mov_b32_e32 v1, s22
	s_nop 0
	v_addc_co_u32_e32 v5, vcc, 0, v1, vcc
	v_mov_b32_e32 v1, 1
	buffer_inv sc1
	flat_atomic_add v1, v[4:5], v1 offset:1024 sc0
	v_cvt_f32_u32_e32 v3, v2
	v_sub_u32_e32 v4, 0, v2
	v_rcp_iflag_f32_e32 v3, v3
	s_nop 0
	v_mul_f32_e32 v3, 0x4f7ffffe, v3
	v_cvt_u32_f32_e32 v3, v3
	v_mul_lo_u32 v4, v4, v3
	v_mul_hi_u32 v4, v3, v4
	v_add_u32_e32 v3, v3, v4
	s_waitcnt vmcnt(0) lgkmcnt(0)
	v_mul_hi_u32 v3, v1, v3
	v_mul_lo_u32 v5, v3, v2
	v_add_u32_e32 v4, 1, v1
	v_sub_u32_e32 v1, v1, v5
	v_add_u32_e32 v6, 1, v3
	v_cmp_ge_u32_e32 vcc, v1, v2
	v_sub_u32_e32 v5, v1, v2
	s_nop 0
	v_cndmask_b32_e32 v3, v3, v6, vcc
	v_cndmask_b32_e32 v1, v1, v5, vcc
	v_add_u32_e32 v5, 1, v3
	v_cmp_ge_u32_e32 vcc, v1, v2
	s_nop 1
	v_cndmask_b32_e32 v1, v3, v5, vcc
	v_mad_u64_u32 v[2:3], s[0:1], v2, v1, v[2:3]
	v_cmp_ne_u32_e32 vcc, v4, v2
	s_and_saveexec_b64 s[0:1], vcc
	s_xor_b64 s[0:1], exec, s[0:1]
	s_cbranch_execz .LBB0_72
	v_mov_b32_e32 v0, s23
	v_add_co_u32_e32 v2, vcc, 0x2000, v0
	v_mov_b32_e32 v0, s22
	s_nop 0
	v_addc_co_u32_e32 v3, vcc, 0, v0, vcc
	flat_load_dword v0, v[2:3] offset:1024 sc1
	s_add_u32 s6, s23, 0x2400
	s_addc_u32 s7, s22, 0
	s_waitcnt vmcnt(0) lgkmcnt(0)
	v_cmp_eq_u32_e32 vcc, v0, v1
	s_and_saveexec_b64 s[4:5], vcc
	s_cbranch_execz .LBB0_71
	s_mov_b32 s24, 1
	s_mov_b64 s[8:9], 0
	s_branch .LBB0_63

; __device__ __forceinline__ unsigned xb_ld(unsigned* p)              { return __hip_atomic_load(p, __ATOMIC_RELAXED, __HIP_MEMORY_SCOPE_AGENT); }
; __device__ __forceinline__ unsigned xb_add(unsigned* p, unsigned v) { return __hip_atomic_fetch_add(p, v, __ATOMIC_RELAXED, __HIP_MEMORY_SCOPE_AGENT); }
; #define XB_SPIN(cond, bar) do { unsigned _sp = 0; while (cond) { __builtin_amdgcn_s_sleep(1); \
;     if ((++_sp & 255u) == 0u) { if (xb_ld(&(bar)[XB_TMO])) break; if (_sp > XB_SPIN_CAP) { atomicAdd(&(bar)[XB_TMO], 1u); break; } } } } while (0)
; __device__ __forceinline__ void xcd_barrier(const XcdBarrier& b) {
;     ...
;         const unsigned old = xb_add(&bar[XB_XSUB(b.x)], 1u);
;         const unsigned gen = old / nloc;
;         if (old + 1u == (gen + 1u) * nloc) {
;             __builtin_amdgcn_fence(__ATOMIC_RELEASE, "agent");
;             asm volatile("s_waitcnt vmcnt(0)" ::: "memory");
;             const unsigned og = xb_add(&bar[XB_TOP], 1u);
;             const unsigned tg = og / nx;
;             if (og + 1u == (tg + 1u) * nx) xb_add(&bar[XB_TOPGEN], 1u);
;             else XB_SPIN(xb_ld(&bar[XB_TOPGEN]) == tg, bar);
.LBB0_71:
	s_or_b64 exec, exec, s[4:5]
	s_waitcnt vmcnt(0) lgkmcnt(0)
	s_waitcnt vmcnt(0)
.LBB0_72:
	s_andn2_saveexec_b64 s[0:1], s[0:1]
	s_cbranch_execz .LBB0_88
	v_mov_b32_e32 v1, s36
	v_add_co_u32_e32 v2, vcc, 0x3000, v1
	v_mov_b32_e32 v1, s37
	s_waitcnt vmcnt(0)
	v_addc_co_u32_e32 v3, vcc, 0, v1, vcc
	v_mov_b32_e32 v1, 1
	flat_atomic_add v1, v[2:3], v1 offset:1024 sc0
	v_cvt_f32_u32_e32 v2, v0
	v_sub_u32_e32 v3, 0, v0
	s_add_u32 s0, s36, 0x3500
	s_addc_u32 s1, s37, 0
	v_rcp_iflag_f32_e32 v2, v2
	s_mov_b64 s[6:7], -1
	v_mul_f32_e32 v2, 0x4f7ffffe, v2
	v_cvt_u32_f32_e32 v2, v2
	v_mul_lo_u32 v3, v3, v2
	v_mul_hi_u32 v3, v2, v3
	v_add_u32_e32 v2, v2, v3
	s_waitcnt vmcnt(0) lgkmcnt(0)
	v_mul_hi_u32 v2, v1, v2
	v_mul_lo_u32 v4, v2, v0
	v_add_u32_e32 v3, 1, v1
	v_sub_u32_e32 v1, v1, v4
	v_add_u32_e32 v5, 1, v2
	v_cmp_ge_u32_e32 vcc, v1, v0
	v_sub_u32_e32 v4, v1, v0
	s_nop 0
	v_cndmask_b32_e32 v2, v2, v5, vcc
	v_cndmask_b32_e32 v1, v1, v4, vcc
	v_add_u32_e32 v4, 1, v2
	v_cmp_ge_u32_e32 vcc, v1, v0
	s_nop 1
	v_cndmask_b32_e32 v2, v2, v4, vcc
	v_mad_u64_u32 v[0:1], s[4:5], v0, v2, v[0:1]
	v_cmp_ne_u32_e32 vcc, v3, v0
	v_mov_b64_e32 v[0:1], s[0:1]
	s_and_saveexec_b64 s[4:5], vcc
	s_cbranch_execz .LBB0_85
	v_mov_b64_e32 v[0:1], s[0:1]
	flat_load_dword v0, v[0:1] sc1
	s_mov_b64 s[10:11], 0
	s_waitcnt vmcnt(0) lgkmcnt(0)
	v_cmp_eq_u32_e32 vcc, v0, v2
	s_and_saveexec_b64 s[8:9], vcc
	s_cbranch_execz .LBB0_84
	s_add_u32 s6, s36, 0x200
	s_addc_u32 s7, s37, 0
	s_mov_b32 s24, 1
	s_branch .LBB0_77

; __device__ __forceinline__ unsigned xb_ld(unsigned* p)              { return __hip_atomic_load(p, __ATOMIC_RELAXED, __HIP_MEMORY_SCOPE_AGENT); }
; __device__ __forceinline__ unsigned xb_add(unsigned* p, unsigned v) { return __hip_atomic_fetch_add(p, v, __ATOMIC_RELAXED, __HIP_MEMORY_SCOPE_AGENT); }
; #define XB_SPIN(cond, bar) do { unsigned _sp = 0; while (cond) { __builtin_amdgcn_s_sleep(1); \
;     if ((++_sp & 255u) == 0u) { if (xb_ld(&(bar)[XB_TMO])) break; if (_sp > XB_SPIN_CAP) { atomicAdd(&(bar)[XB_TMO], 1u); break; } } } } while (0)
; __device__ __forceinline__ void xcd_barrier(const XcdBarrier& b) {
;     ...
;             else XB_SPIN(xb_ld(&bar[XB_TOPGEN]) == tg, bar);
;             __builtin_amdgcn_fence(__ATOMIC_ACQUIRE, "agent");
;             xb_add(&bar[XB_XGEN(b.x)], 1u);
;             asm volatile("s_waitcnt vmcnt(0)" ::: "memory");
.LBB0_87:
	s_or_b64 exec, exec, s[0:1]
	v_mov_b32_e32 v0, s23
	v_add_co_u32_e32 v0, vcc, 0x2000, v0
	v_mov_b32_e32 v1, s22
	s_nop 0
	v_addc_co_u32_e32 v1, vcc, 0, v1, vcc
	v_mov_b32_e32 v2, 1
	s_waitcnt vmcnt(0) lgkmcnt(0)
	flat_atomic_add v[0:1], v2 offset:1024
	s_waitcnt vmcnt(0)
